# P2 V re-layout item rewritten: 16-byte loads + wave-private LDS transpose (ds_write_b16 / ds_read_b64) instead of 32 two-byte gathers per tile
# speedup vs baseline: 1.0041x; 1.0013x over previous
.LBB0_317:
	s_cmpk_gt_i32 s42, 0x7f
	s_mov_b64 s[0:1], -1
	s_cbranch_scc0 .LBB0_389
	s_cmpk_gt_u32 s42, 0xff
	s_cbranch_scc0 .LBB0_384
	v_lshl_add_u32 v6, s42, 4, v68
	s_nop 0
	v_readfirstlane_b32 s98, v6
	s_add_u32 s44, s98, 0
	s_cmpk_lt_u32 s44, 0x9000
	s_cbranch_scc0 .Lrl_0_b
	s_cmpk_ge_u32 s44, 0x3000
	s_cselect_b32 s49, 1, 0
	s_cmpk_ge_u32 s44, 0x6000
	s_cselect_b32 s50, 1, 0
	s_add_u32 s49, s49, s50
	s_mul_i32 s50, s49, 0x3000
	s_sub_u32 s45, s44, s50
	s_lshr_b32 s50, s45, 8
	s_mul_hi_u32 s51, s50, 0x2aaaaaab
	s_mul_i32 s38, s51, 6
	s_sub_u32 s38, s50, s38
	s_lshl_b32 s47, s38, 6
	s_addk_i32 s47, 0x300
	s_lshl_b32 s46, s51, 12
	s_cmp_eq_u32 s49, 0
	s_cbranch_scc0 .Lrl_0_w1
	s_bfe_u32 s38, s45, 0x70001
	s_lshl_b32 s38, s38, 5
	s_add_u32 s46, s46, s38
	s_movk_i32 s48, 0x1c00
	s_branch .Lrl_0_a
.Lrl_0_w1:
	s_cmp_eq_u32 s49, 1
	s_cbranch_scc0 .Lrl_0_w2
	s_bfe_u32 s38, s45, 0x50001
	s_lshl_b32 s38, s38, 7
	s_add_u32 s46, s46, s38
	s_bfe_u32 s38, s45, 0x20006
	s_add_u32 s46, s46, s38
	s_movk_i32 s48, 0x7000
	s_branch .Lrl_0_a
.Lrl_0_w2:
	s_bfe_u32 s38, s45, 0x30001
	s_lshl_b32 s38, s38, 9
	s_add_u32 s46, s46, s38
	s_bfe_u32 s38, s45, 0x40004
	s_add_u32 s46, s46, s38
	s_mov_b32 s48, 0x1c000
.Lrl_0_a:
	s_lshl_b32 s39, s49, 1
	s_add_u32 s39, s39, 2
	s_branch .Lrl_0_c
.Lrl_0_b:
	s_cmpk_lt_u32 s44, 0xa000
	s_cbranch_scc0 .Lrl_0_v
	s_sub_u32 s45, s44, 0x9000
	s_lshr_b32 s49, s45, 11
	s_and_b32 s45, s45, 0x7ff
	s_cmp_eq_u32 s49, 0
	s_movk_i32 s47, 0x840
	s_cselect_b32 s47, 0x7c0, s47
	s_lshr_b32 s46, s45, 8
	s_lshl_b32 s46, s46, 12
	s_bfe_u32 s38, s45, 0x70001
	s_lshl_b32 s38, s38, 5
	s_add_u32 s46, s46, s38
	s_movk_i32 s48, 0x1c00
	s_lshl_b32 s39, s49, 1
	s_add_u32 s39, s39, 8
	s_branch .Lrl_0_c
.Lrl_0_v:
	s_sub_u32 s45, s44, 0xa000
	s_lshr_b32 s50, s45, 8
	s_and_b32 s38, s50, 3
	s_lshl_b32 s47, s38, 6
	s_addk_i32 s47, 0xb80
	s_lshr_b32 s46, s50, 2
	s_lshl_b32 s46, s46, 12
	s_bfe_u32 s38, s45, 0x70001
	s_lshl_b32 s38, s38, 5
	s_add_u32 s46, s46, s38
	s_movk_i32 s48, 0x1c00
	s_movk_i32 s39, 12
.Lrl_0_c:
	s_and_b32 s38, s45, 1
	s_lshl_b32 s38, s38, 5
	s_add_u32 s47, s47, s38
	s_mul_i32 s46, s46, 0x1c00
	s_lshl_b32 s47, s47, 1
	s_add_u32 s46, s46, s47
	s_nop 0
	v_readlane_b32 s36, v253, s39
	s_add_u32 s39, s39, 1
	s_nop 0
	v_readlane_b32 s37, v253, s39
	s_lshl_b32 s38, s45, 11
	s_add_u32 s36, s36, s38
	s_addc_u32 s37, s37, 0
	v_writelane_b32 v8, s46, 0
	v_writelane_b32 v8, s48, 1
	v_writelane_b32 v8, s36, 2
	v_writelane_b32 v8, s37, 3
	s_add_u32 s44, s98, 1
	s_cmpk_lt_u32 s44, 0x9000
	s_cbranch_scc0 .Lrl_1_b
	s_cmpk_ge_u32 s44, 0x3000
	s_cselect_b32 s49, 1, 0
	s_cmpk_ge_u32 s44, 0x6000
	s_cselect_b32 s50, 1, 0
	s_add_u32 s49, s49, s50
	s_mul_i32 s50, s49, 0x3000
	s_sub_u32 s45, s44, s50
	s_lshr_b32 s50, s45, 8
	s_mul_hi_u32 s51, s50, 0x2aaaaaab
	s_mul_i32 s38, s51, 6
	s_sub_u32 s38, s50, s38
	s_lshl_b32 s47, s38, 6
	s_addk_i32 s47, 0x300
	s_lshl_b32 s46, s51, 12
	s_cmp_eq_u32 s49, 0
	s_cbranch_scc0 .Lrl_1_w1
	s_bfe_u32 s38, s45, 0x70001
	s_lshl_b32 s38, s38, 5
	s_add_u32 s46, s46, s38
	s_movk_i32 s48, 0x1c00
	s_branch .Lrl_1_a

.Lrl_1_c:
	s_and_b32 s38, s45, 1
	s_lshl_b32 s38, s38, 5
	s_add_u32 s47, s47, s38
	s_mul_i32 s46, s46, 0x1c00
	s_lshl_b32 s47, s47, 1
	s_add_u32 s46, s46, s47
	s_nop 0
	v_readlane_b32 s36, v253, s39
	s_add_u32 s39, s39, 1
	s_nop 0
	v_readlane_b32 s37, v253, s39
	s_lshl_b32 s38, s45, 11
	s_add_u32 s36, s36, s38
	s_addc_u32 s37, s37, 0
	v_writelane_b32 v8, s46, 4
	v_writelane_b32 v8, s48, 5
	v_writelane_b32 v8, s36, 6
	v_writelane_b32 v8, s37, 7
	s_add_u32 s44, s98, 2
	s_cmpk_lt_u32 s44, 0x9000
	s_cbranch_scc0 .Lrl_2_b
	s_cmpk_ge_u32 s44, 0x3000
	s_cselect_b32 s49, 1, 0
	s_cmpk_ge_u32 s44, 0x6000
	s_cselect_b32 s50, 1, 0
	s_add_u32 s49, s49, s50
	s_mul_i32 s50, s49, 0x3000
	s_sub_u32 s45, s44, s50
	s_lshr_b32 s50, s45, 8
	s_mul_hi_u32 s51, s50, 0x2aaaaaab
	s_mul_i32 s38, s51, 6
	s_sub_u32 s38, s50, s38
	s_lshl_b32 s47, s38, 6
	s_addk_i32 s47, 0x300
	s_lshl_b32 s46, s51, 12
	s_cmp_eq_u32 s49, 0
	s_cbranch_scc0 .Lrl_2_w1
	s_bfe_u32 s38, s45, 0x70001
	s_lshl_b32 s38, s38, 5
	s_add_u32 s46, s46, s38
	s_movk_i32 s48, 0x1c00
	s_branch .Lrl_2_a

.Lrl_2_c:
	s_and_b32 s38, s45, 1
	s_lshl_b32 s38, s38, 5
	s_add_u32 s47, s47, s38
	s_mul_i32 s46, s46, 0x1c00
	s_lshl_b32 s47, s47, 1
	s_add_u32 s46, s46, s47
	s_nop 0
	v_readlane_b32 s36, v253, s39
	s_add_u32 s39, s39, 1
	s_nop 0
	v_readlane_b32 s37, v253, s39
	s_lshl_b32 s38, s45, 11
	s_add_u32 s36, s36, s38
	s_addc_u32 s37, s37, 0
	v_writelane_b32 v8, s46, 8
	v_writelane_b32 v8, s48, 9
	v_writelane_b32 v8, s36, 10
	v_writelane_b32 v8, s37, 11
	s_add_u32 s44, s98, 3
	s_cmpk_lt_u32 s44, 0x9000
	s_cbranch_scc0 .Lrl_3_b
	s_cmpk_ge_u32 s44, 0x3000
	s_cselect_b32 s49, 1, 0
	s_cmpk_ge_u32 s44, 0x6000
	s_cselect_b32 s50, 1, 0
	s_add_u32 s49, s49, s50
	s_mul_i32 s50, s49, 0x3000
	s_sub_u32 s45, s44, s50
	s_lshr_b32 s50, s45, 8
	s_mul_hi_u32 s51, s50, 0x2aaaaaab
	s_mul_i32 s38, s51, 6
	s_sub_u32 s38, s50, s38
	s_lshl_b32 s47, s38, 6
	s_addk_i32 s47, 0x300
	s_lshl_b32 s46, s51, 12
	s_cmp_eq_u32 s49, 0
	s_cbranch_scc0 .Lrl_3_w1
	s_bfe_u32 s38, s45, 0x70001
	s_lshl_b32 s38, s38, 5
	s_add_u32 s46, s46, s38
	s_movk_i32 s48, 0x1c00
	s_branch .Lrl_3_a

.Lrl_3_c:
	s_and_b32 s38, s45, 1
	s_lshl_b32 s38, s38, 5
	s_add_u32 s47, s47, s38
	s_mul_i32 s46, s46, 0x1c00
	s_lshl_b32 s47, s47, 1
	s_add_u32 s46, s46, s47
	s_nop 0
	v_readlane_b32 s36, v253, s39
	s_add_u32 s39, s39, 1
	s_nop 0
	v_readlane_b32 s37, v253, s39
	s_lshl_b32 s38, s45, 11
	s_add_u32 s36, s36, s38
	s_addc_u32 s37, s37, 0
	v_writelane_b32 v8, s46, 12
	v_writelane_b32 v8, s48, 13
	v_writelane_b32 v8, s36, 14
	v_writelane_b32 v8, s37, 15
	v_and_b32_e32 v2, 63, v199
	v_lshrrev_b32_e32 v3, 2, v2
	v_and_b32_e32 v4, 3, v2
	v_lshrrev_b32_e32 v9, 6, v199
	v_mul_u32_u24_e32 v9, 0x2400, v9
	v_mul_u32_u24_e32 v5, 0x240, v4
	v_lshl_add_u32 v5, v3, 1, v5
	v_add_u32_e32 v5, v5, v9
	v_and_b32_e32 v6, 31, v2
	v_mul_u32_u24_e32 v6, 72, v6
	v_lshrrev_b32_e32 v10, 5, v2
	v_lshl_add_u32 v6, v10, 3, v6
	v_add_u32_e32 v6, v6, v9
	v_lshlrev_b32_e32 v4, 4, v4
	v_lshlrev_b32_e32 v7, 4, v2
	v_readlane_b32 s46, v8, 0
	v_readlane_b32 s48, v8, 1
	s_nop 1
	v_mul_lo_u32 v52, v3, s48
	s_lshl_b32 s49, s48, 4
	v_add3_u32 v52, v52, s46, v4
	v_add_u32_e32 v53, s49, v52
	global_load_dwordx4 v[12:15], v52, s[66:67]
	global_load_dwordx4 v[16:19], v53, s[66:67]
	v_readlane_b32 s46, v8, 4
	v_readlane_b32 s48, v8, 5
	s_nop 1
	v_mul_lo_u32 v54, v3, s48
	s_lshl_b32 s49, s48, 4
	v_add3_u32 v54, v54, s46, v4
	v_add_u32_e32 v55, s49, v54
	global_load_dwordx4 v[20:23], v54, s[66:67]
	global_load_dwordx4 v[24:27], v55, s[66:67]
	v_readlane_b32 s46, v8, 8
	v_readlane_b32 s48, v8, 9
	s_nop 1
	v_mul_lo_u32 v56, v3, s48
	s_lshl_b32 s49, s48, 4
	v_add3_u32 v56, v56, s46, v4
	v_add_u32_e32 v57, s49, v56
	global_load_dwordx4 v[28:31], v56, s[66:67]
	global_load_dwordx4 v[32:35], v57, s[66:67]
	v_readlane_b32 s46, v8, 12
	v_readlane_b32 s48, v8, 13
	s_nop 1
	v_mul_lo_u32 v58, v3, s48
	s_lshl_b32 s49, s48, 4
	v_add3_u32 v58, v58, s46, v4
	v_add_u32_e32 v59, s49, v58
	global_load_dwordx4 v[36:39], v58, s[66:67]
	global_load_dwordx4 v[40:43], v59, s[66:67]
	s_waitcnt vmcnt(6)
	ds_write_b16 v5, v12 offset:0
	ds_write_b16_d16_hi v5, v12 offset:72
	ds_write_b16 v5, v13 offset:144
	ds_write_b16_d16_hi v5, v13 offset:216
	ds_write_b16 v5, v14 offset:288
	ds_write_b16_d16_hi v5, v14 offset:360
	ds_write_b16 v5, v15 offset:432
	ds_write_b16_d16_hi v5, v15 offset:504
	ds_write_b16 v5, v16 offset:32
	ds_write_b16_d16_hi v5, v16 offset:104
	ds_write_b16 v5, v17 offset:176
	ds_write_b16_d16_hi v5, v17 offset:248
	ds_write_b16 v5, v18 offset:320
	ds_write_b16_d16_hi v5, v18 offset:392
	ds_write_b16 v5, v19 offset:464
	ds_write_b16_d16_hi v5, v19 offset:536
	s_waitcnt vmcnt(4)
	ds_write_b16 v5, v20 offset:2304
	ds_write_b16_d16_hi v5, v20 offset:2376
	ds_write_b16 v5, v21 offset:2448
	ds_write_b16_d16_hi v5, v21 offset:2520
	ds_write_b16 v5, v22 offset:2592
	ds_write_b16_d16_hi v5, v22 offset:2664
	ds_write_b16 v5, v23 offset:2736
	ds_write_b16_d16_hi v5, v23 offset:2808
	ds_write_b16 v5, v24 offset:2336
	ds_write_b16_d16_hi v5, v24 offset:2408
	ds_write_b16 v5, v25 offset:2480
	ds_write_b16_d16_hi v5, v25 offset:2552
	ds_write_b16 v5, v26 offset:2624
	ds_write_b16_d16_hi v5, v26 offset:2696
	ds_write_b16 v5, v27 offset:2768
	ds_write_b16_d16_hi v5, v27 offset:2840
	s_waitcnt vmcnt(2)
	ds_write_b16 v5, v28 offset:4608
	ds_write_b16_d16_hi v5, v28 offset:4680
	ds_write_b16 v5, v29 offset:4752
	ds_write_b16_d16_hi v5, v29 offset:4824
	ds_write_b16 v5, v30 offset:4896
	ds_write_b16_d16_hi v5, v30 offset:4968
	ds_write_b16 v5, v31 offset:5040
	ds_write_b16_d16_hi v5, v31 offset:5112
	ds_write_b16 v5, v32 offset:4640
	ds_write_b16_d16_hi v5, v32 offset:4712
	ds_write_b16 v5, v33 offset:4784
	ds_write_b16_d16_hi v5, v33 offset:4856
	ds_write_b16 v5, v34 offset:4928
	ds_write_b16_d16_hi v5, v34 offset:5000
	ds_write_b16 v5, v35 offset:5072
	ds_write_b16_d16_hi v5, v35 offset:5144
	s_waitcnt vmcnt(0)
	ds_write_b16 v5, v36 offset:6912
	ds_write_b16_d16_hi v5, v36 offset:6984
	ds_write_b16 v5, v37 offset:7056
	ds_write_b16_d16_hi v5, v37 offset:7128
	ds_write_b16 v5, v38 offset:7200
	ds_write_b16_d16_hi v5, v38 offset:7272
	ds_write_b16 v5, v39 offset:7344
	ds_write_b16_d16_hi v5, v39 offset:7416
	ds_write_b16 v5, v40 offset:6944
	ds_write_b16_d16_hi v5, v40 offset:7016
	ds_write_b16 v5, v41 offset:7088
	ds_write_b16_d16_hi v5, v41 offset:7160
	ds_write_b16 v5, v42 offset:7232
	ds_write_b16_d16_hi v5, v42 offset:7304
	ds_write_b16 v5, v43 offset:7376
	ds_write_b16_d16_hi v5, v43 offset:7448
	s_waitcnt lgkmcnt(0)
	ds_read_b64 v[12:13], v6 offset:0
	ds_read_b64 v[14:15], v6 offset:16
	ds_read_b64 v[16:17], v6 offset:32
	ds_read_b64 v[18:19], v6 offset:48
	ds_read_b64 v[20:21], v6 offset:2304
	ds_read_b64 v[22:23], v6 offset:2320
	ds_read_b64 v[24:25], v6 offset:2336
	ds_read_b64 v[26:27], v6 offset:2352
	ds_read_b64 v[28:29], v6 offset:4608
	ds_read_b64 v[30:31], v6 offset:4624
	ds_read_b64 v[32:33], v6 offset:4640
	ds_read_b64 v[34:35], v6 offset:4656
	v_readlane_b32 s36, v8, 2
	v_readlane_b32 s37, v8, 3
	s_waitcnt lgkmcnt(8)
	s_nop 3
	global_store_dwordx4 v7, v[12:15], s[36:37]
	global_store_dwordx4 v7, v[16:19], s[36:37] offset:1024
	ds_read_b64 v[36:37], v6 offset:6912
	ds_read_b64 v[38:39], v6 offset:6928
	ds_read_b64 v[40:41], v6 offset:6944
	ds_read_b64 v[42:43], v6 offset:6960
	v_readlane_b32 s36, v8, 6
	v_readlane_b32 s37, v8, 7
	s_waitcnt lgkmcnt(8)
	s_nop 3
	global_store_dwordx4 v7, v[20:23], s[36:37]
	global_store_dwordx4 v7, v[24:27], s[36:37] offset:1024
	v_readlane_b32 s36, v8, 10
	v_readlane_b32 s37, v8, 11
	s_waitcnt lgkmcnt(4)
	s_nop 3
	global_store_dwordx4 v7, v[28:31], s[36:37]
	global_store_dwordx4 v7, v[32:35], s[36:37] offset:1024
	v_readlane_b32 s36, v8, 14
	v_readlane_b32 s37, v8, 15
	s_waitcnt lgkmcnt(0)
	s_nop 3
	global_store_dwordx4 v7, v[36:39], s[36:37]
	global_store_dwordx4 v7, v[40:43], s[36:37] offset:1024
	s_mov_b64 s[0:1], 0
